# stack: sc1 write-through epilogue stores + batched scan2 carry fold + grid-barrier acquire invalidate issued right after arrival (overlaps the wait)
# speedup vs baseline: 1.0132x; 1.0132x over previous
; __device__ __forceinline__ unsigned xb_add(unsigned* p, unsigned v) { return __hip_atomic_fetch_add(p, v, __ATOMIC_RELAXED, __HIP_MEMORY_SCOPE_AGENT); }
; __device__ __forceinline__ void xcd_barrier(const XcdBarrier& b, bool leader) {
;     ...
;     if (leader) {
;         unsigned* bar = b.bar;
;         __builtin_amdgcn_s_waitcnt(0);
;         unsigned nloc = b.st[0], nx = b.st[1];
;         if (nloc == 0u) { xcd_barrier_complete(bar, b.x, nloc, nx); b.st[0] = nloc; b.st[1] = nx; }
;         const unsigned old = xb_add(&bar[XB_XSUB(b.x)], 1u);
;         const unsigned gen = old / nloc;
;         if (old + 1u == (gen + 1u) * nloc) {
;             __builtin_amdgcn_fence(__ATOMIC_RELEASE, "agent");
;             asm volatile("s_waitcnt vmcnt(0)" ::: "memory");
;             const unsigned og = xb_add(&bar[XB_TOP], 1u);
;             const unsigned tg = og / nx;
;             if (og + 1u == (tg + 1u) * nx) xb_add(&bar[XB_TOPGEN], 1u);
.LBB0_71:
	s_or_b64 exec, exec, s[6:7]
	v_cvt_f32_u32_e32 v4, v2
	s_waitcnt vmcnt(0)
	buffer_inv sc1
	v_readfirstlane_b32 s0, v3
	v_sub_u32_e32 v3, 0, v2
	v_rcp_iflag_f32_e32 v4, v4
	v_add_u32_e32 v5, s0, v0
	v_mul_f32_e32 v4, 0x4f7ffffe, v4
	v_cvt_u32_f32_e32 v4, v4
	v_mul_lo_u32 v0, v3, v4
	v_mul_hi_u32 v0, v4, v0
	v_add_u32_e32 v0, v4, v0
	v_mul_hi_u32 v0, v5, v0
	v_mul_lo_u32 v3, v0, v2
	v_sub_u32_e32 v3, v5, v3
	v_add_u32_e32 v4, 1, v0
	v_cmp_ge_u32_e32 vcc, v3, v2
	s_nop 1
	v_cndmask_b32_e32 v0, v0, v4, vcc
	v_sub_u32_e32 v4, v3, v2
	v_cndmask_b32_e32 v3, v3, v4, vcc
	v_add_u32_e32 v4, 1, v0
	v_cmp_ge_u32_e32 vcc, v3, v2
	v_add_u32_e32 v3, 1, v5
	s_nop 0
	v_cndmask_b32_e32 v0, v0, v4, vcc
	v_mul_lo_u32 v4, v2, v0
	v_add_u32_e32 v2, v4, v2
	v_cmp_eq_u32_e32 vcc, v3, v2
	s_and_saveexec_b64 s[6:7], vcc
	s_cbranch_execz .LBB0_77
	s_mov_b64 s[8:9], exec
	buffer_wbl2 sc1
	s_waitcnt lgkmcnt(0)
	s_waitcnt vmcnt(0)
	v_mbcnt_lo_u32_b32 v2, s8, 0
	v_mbcnt_hi_u32_b32 v2, s9, v2
	v_cmp_eq_u32_e32 vcc, 0, v2
	s_and_saveexec_b64 s[10:11], vcc
	s_cbranch_execz .LBB0_74
	s_bcnt1_i32_b64 s0, s[8:9]
	v_mov_b32_e32 v3, 0x3000
	v_mov_b32_e32 v4, s0
	global_atomic_add v3, v3, v4, s[90:91] offset:1024 sc0

; __device__ __forceinline__ unsigned xb_ld(unsigned* p)              { return __hip_atomic_load(p, __ATOMIC_RELAXED, __HIP_MEMORY_SCOPE_AGENT); }
; #define XB_SPIN(cond, bar) do { unsigned _sp = 0; while (cond) { __builtin_amdgcn_s_sleep(1); \
;     if ((++_sp & 255u) == 0u) { if (xb_ld(&(bar)[XB_TMO])) break; if (_sp > XB_SPIN_CAP) { atomicAdd(&(bar)[XB_TMO], 1u); break; } } } } while (0)
; __device__ __forceinline__ void xcd_barrier(const XcdBarrier& b, bool leader) {
;     ...
;         XB_SPIN(xb_ld(&bar[XB_TOPGEN]) == gen, bar);
;         __builtin_amdgcn_fence(__ATOMIC_ACQUIRE, "agent");
;         asm volatile("s_waitcnt vmcnt(0)" ::: "memory");
.LBB0_89:
	s_or_b64 exec, exec, s[6:7]
	s_waitcnt vmcnt(0)
	s_waitcnt vmcnt(0)

; __device__ __forceinline__ unsigned xb_add(unsigned* p, unsigned v) { return __hip_atomic_fetch_add(p, v, __ATOMIC_RELAXED, __HIP_MEMORY_SCOPE_AGENT); }
; __device__ __forceinline__ void xcd_barrier(const XcdBarrier& b, bool leader) {
;     ...
;         const unsigned old = xb_add(&bar[XB_XSUB(b.x)], 1u);
;         const unsigned gen = old / nloc;
;         if (old + 1u == (gen + 1u) * nloc) {
;             __builtin_amdgcn_fence(__ATOMIC_RELEASE, "agent");
;             asm volatile("s_waitcnt vmcnt(0)" ::: "memory");
;             const unsigned og = xb_add(&bar[XB_TOP], 1u);
;             const unsigned tg = og / nx;
;             if (og + 1u == (tg + 1u) * nx) xb_add(&bar[XB_TOPGEN], 1u);
.LBB0_179:
	s_or_b64 exec, exec, s[6:7]
	v_cvt_f32_u32_e32 v4, v2
	s_waitcnt vmcnt(0)
	buffer_inv sc1
	v_readfirstlane_b32 s6, v3
	v_sub_u32_e32 v3, 0, v2
	v_rcp_iflag_f32_e32 v4, v4
	v_add_u32_e32 v5, s6, v0
	v_mul_f32_e32 v4, 0x4f7ffffe, v4
	v_cvt_u32_f32_e32 v4, v4
	v_mul_lo_u32 v0, v3, v4
	v_mul_hi_u32 v0, v4, v0
	v_add_u32_e32 v0, v4, v0
	v_mul_hi_u32 v0, v5, v0
	v_mul_lo_u32 v3, v0, v2
	v_sub_u32_e32 v3, v5, v3
	v_add_u32_e32 v4, 1, v0
	v_cmp_ge_u32_e32 vcc, v3, v2
	s_nop 1
	v_cndmask_b32_e32 v0, v0, v4, vcc
	v_sub_u32_e32 v4, v3, v2
	v_cndmask_b32_e32 v3, v3, v4, vcc
	v_add_u32_e32 v4, 1, v0
	v_cmp_ge_u32_e32 vcc, v3, v2
	v_add_u32_e32 v3, 1, v5
	s_nop 0
	v_cndmask_b32_e32 v0, v0, v4, vcc
	v_mul_lo_u32 v4, v2, v0
	v_add_u32_e32 v2, v4, v2
	v_cmp_eq_u32_e32 vcc, v3, v2
	s_and_saveexec_b64 s[6:7], vcc
	s_cbranch_execz .LBB0_185
	s_mov_b64 s[10:11], exec
	buffer_wbl2 sc1
	s_waitcnt lgkmcnt(0)
	s_waitcnt vmcnt(0)
	v_mbcnt_lo_u32_b32 v2, s10, 0
	v_mbcnt_hi_u32_b32 v2, s11, v2
	v_cmp_eq_u32_e32 vcc, 0, v2
	s_and_saveexec_b64 s[12:13], vcc
	s_cbranch_execz .LBB0_182
	s_bcnt1_i32_b64 s10, s[10:11]
	v_mov_b32_e32 v3, 0x3000
	v_mov_b32_e32 v4, s10
	global_atomic_add v3, v3, v4, s[90:91] offset:1024 sc0

; __device__ __forceinline__ unsigned xb_add(unsigned* p, unsigned v) { return __hip_atomic_fetch_add(p, v, __ATOMIC_RELAXED, __HIP_MEMORY_SCOPE_AGENT); }
; __device__ __forceinline__ void xcd_barrier(const XcdBarrier& b, bool leader) {
;     ...
;         const unsigned old = xb_add(&bar[XB_XSUB(b.x)], 1u);
;         const unsigned gen = old / nloc;
;         if (old + 1u == (gen + 1u) * nloc) {
;             __builtin_amdgcn_fence(__ATOMIC_RELEASE, "agent");
;             asm volatile("s_waitcnt vmcnt(0)" ::: "memory");
;             const unsigned og = xb_add(&bar[XB_TOP], 1u);
;             const unsigned tg = og / nx;
;             if (og + 1u == (tg + 1u) * nx) xb_add(&bar[XB_TOPGEN], 1u);
.LBB0_229:
	s_or_b64 exec, exec, s[6:7]
	v_cvt_f32_u32_e32 v4, v2
	s_waitcnt vmcnt(0)
	buffer_inv sc1
	v_readfirstlane_b32 s3, v3
	v_sub_u32_e32 v3, 0, v2
	v_rcp_iflag_f32_e32 v4, v4
	v_add_u32_e32 v5, s3, v0
	v_mul_f32_e32 v4, 0x4f7ffffe, v4
	v_cvt_u32_f32_e32 v4, v4
	v_mul_lo_u32 v0, v3, v4
	v_mul_hi_u32 v0, v4, v0
	v_add_u32_e32 v0, v4, v0
	v_mul_hi_u32 v0, v5, v0
	v_mul_lo_u32 v3, v0, v2
	v_sub_u32_e32 v3, v5, v3
	v_add_u32_e32 v4, 1, v0
	v_cmp_ge_u32_e32 vcc, v3, v2
	s_nop 1
	v_cndmask_b32_e32 v0, v0, v4, vcc
	v_sub_u32_e32 v4, v3, v2
	v_cndmask_b32_e32 v3, v3, v4, vcc
	v_add_u32_e32 v4, 1, v0
	v_cmp_ge_u32_e32 vcc, v3, v2
	v_add_u32_e32 v3, 1, v5
	s_nop 0
	v_cndmask_b32_e32 v0, v0, v4, vcc
	v_mul_lo_u32 v4, v2, v0
	v_add_u32_e32 v2, v4, v2
	v_cmp_eq_u32_e32 vcc, v3, v2
	s_and_saveexec_b64 s[6:7], vcc
	s_cbranch_execz .LBB0_235
	s_mov_b64 s[10:11], exec
	buffer_wbl2 sc1
	s_waitcnt lgkmcnt(0)
	s_waitcnt vmcnt(0)
	v_mbcnt_lo_u32_b32 v2, s10, 0
	v_mbcnt_hi_u32_b32 v2, s11, v2
	v_cmp_eq_u32_e32 vcc, 0, v2
	s_and_saveexec_b64 s[12:13], vcc
	s_cbranch_execz .LBB0_232
	s_bcnt1_i32_b64 s3, s[10:11]
	v_mov_b32_e32 v3, 0x3000
	v_mov_b32_e32 v4, s3
	global_atomic_add v3, v3, v4, s[90:91] offset:1024 sc0

; __device__ __forceinline__ unsigned xb_add(unsigned* p, unsigned v) { return __hip_atomic_fetch_add(p, v, __ATOMIC_RELAXED, __HIP_MEMORY_SCOPE_AGENT); }
; __device__ __forceinline__ void xcd_barrier(const XcdBarrier& b, bool leader) {
;     ...
;         const unsigned old = xb_add(&bar[XB_XSUB(b.x)], 1u);
;         const unsigned gen = old / nloc;
;         if (old + 1u == (gen + 1u) * nloc) {
;             __builtin_amdgcn_fence(__ATOMIC_RELEASE, "agent");
;             asm volatile("s_waitcnt vmcnt(0)" ::: "memory");
;             const unsigned og = xb_add(&bar[XB_TOP], 1u);
;             const unsigned tg = og / nx;
;             if (og + 1u == (tg + 1u) * nx) xb_add(&bar[XB_TOPGEN], 1u);
.LBB0_322:
	s_or_b64 exec, exec, s[6:7]
	v_cvt_f32_u32_e32 v4, v2
	s_waitcnt vmcnt(0)
	buffer_inv sc1
	v_readfirstlane_b32 s6, v3
	v_sub_u32_e32 v3, 0, v2
	v_rcp_iflag_f32_e32 v4, v4
	v_add_u32_e32 v5, s6, v0
	v_mul_f32_e32 v4, 0x4f7ffffe, v4
	v_cvt_u32_f32_e32 v4, v4
	v_mul_lo_u32 v0, v3, v4
	v_mul_hi_u32 v0, v4, v0
	v_add_u32_e32 v0, v4, v0
	v_mul_hi_u32 v0, v5, v0
	v_mul_lo_u32 v3, v0, v2
	v_sub_u32_e32 v3, v5, v3
	v_add_u32_e32 v4, 1, v0
	v_cmp_ge_u32_e32 vcc, v3, v2
	s_nop 1
	v_cndmask_b32_e32 v0, v0, v4, vcc
	v_sub_u32_e32 v4, v3, v2
	v_cndmask_b32_e32 v3, v3, v4, vcc
	v_add_u32_e32 v4, 1, v0
	v_cmp_ge_u32_e32 vcc, v3, v2
	v_add_u32_e32 v3, 1, v5
	s_nop 0
	v_cndmask_b32_e32 v0, v0, v4, vcc
	v_mul_lo_u32 v4, v2, v0
	v_add_u32_e32 v2, v4, v2
	v_cmp_eq_u32_e32 vcc, v3, v2
	s_and_saveexec_b64 s[6:7], vcc
	s_cbranch_execz .LBB0_328
	s_mov_b64 s[8:9], exec
	buffer_wbl2 sc1
	s_waitcnt lgkmcnt(0)
	s_waitcnt vmcnt(0)
	v_mbcnt_lo_u32_b32 v2, s8, 0
	v_mbcnt_hi_u32_b32 v2, s9, v2
	v_cmp_eq_u32_e32 vcc, 0, v2
	s_and_saveexec_b64 s[10:11], vcc
	s_cbranch_execz .LBB0_325
	s_bcnt1_i32_b64 s8, s[8:9]
	v_mov_b32_e32 v3, 0x3000
	v_mov_b32_e32 v4, s8
	global_atomic_add v3, v3, v4, s[90:91] offset:1024 sc0

; __device__ __forceinline__ unsigned xb_add(unsigned* p, unsigned v) { return __hip_atomic_fetch_add(p, v, __ATOMIC_RELAXED, __HIP_MEMORY_SCOPE_AGENT); }
; __device__ __forceinline__ void xcd_barrier(const XcdBarrier& b, bool leader) {
;     ...
;         const unsigned old = xb_add(&bar[XB_XSUB(b.x)], 1u);
;         const unsigned gen = old / nloc;
;         if (old + 1u == (gen + 1u) * nloc) {
;             __builtin_amdgcn_fence(__ATOMIC_RELEASE, "agent");
;             asm volatile("s_waitcnt vmcnt(0)" ::: "memory");
;             const unsigned og = xb_add(&bar[XB_TOP], 1u);
;             const unsigned tg = og / nx;
;             if (og + 1u == (tg + 1u) * nx) xb_add(&bar[XB_TOPGEN], 1u);
.LBB0_369:
	s_or_b64 exec, exec, s[8:9]
	v_cvt_f32_u32_e32 v4, v2
	s_waitcnt vmcnt(0)
	buffer_inv sc1
	v_readfirstlane_b32 s8, v3
	v_sub_u32_e32 v3, 0, v2
	v_rcp_iflag_f32_e32 v4, v4
	v_add_u32_e32 v5, s8, v0
	v_mul_f32_e32 v4, 0x4f7ffffe, v4
	v_cvt_u32_f32_e32 v4, v4
	v_mul_lo_u32 v0, v3, v4
	v_mul_hi_u32 v0, v4, v0
	v_add_u32_e32 v0, v4, v0
	v_mul_hi_u32 v0, v5, v0
	v_mul_lo_u32 v3, v0, v2
	v_sub_u32_e32 v3, v5, v3
	v_add_u32_e32 v4, 1, v0
	v_cmp_ge_u32_e32 vcc, v3, v2
	s_nop 1
	v_cndmask_b32_e32 v0, v0, v4, vcc
	v_sub_u32_e32 v4, v3, v2
	v_cndmask_b32_e32 v3, v3, v4, vcc
	v_add_u32_e32 v4, 1, v0
	v_cmp_ge_u32_e32 vcc, v3, v2
	v_add_u32_e32 v3, 1, v5
	s_nop 0
	v_cndmask_b32_e32 v0, v0, v4, vcc
	v_mul_lo_u32 v4, v2, v0
	v_add_u32_e32 v2, v4, v2
	v_cmp_eq_u32_e32 vcc, v3, v2
	s_and_saveexec_b64 s[8:9], vcc
	s_cbranch_execz .LBB0_375
	s_mov_b64 s[10:11], exec
	buffer_wbl2 sc1
	s_waitcnt lgkmcnt(0)
	s_waitcnt vmcnt(0)
	v_mbcnt_lo_u32_b32 v2, s10, 0
	v_mbcnt_hi_u32_b32 v2, s11, v2
	v_cmp_eq_u32_e32 vcc, 0, v2
	s_and_saveexec_b64 s[22:23], vcc
	s_cbranch_execz .LBB0_372
	s_bcnt1_i32_b64 s10, s[10:11]
	v_mov_b32_e32 v3, 0x3000
	v_mov_b32_e32 v4, s10
	global_atomic_add v3, v3, v4, s[90:91] offset:1024 sc0

; __device__ __forceinline__ unsigned xb_ld(unsigned* p)              { return __hip_atomic_load(p, __ATOMIC_RELAXED, __HIP_MEMORY_SCOPE_AGENT); }
; #define XB_SPIN(cond, bar) do { unsigned _sp = 0; while (cond) { __builtin_amdgcn_s_sleep(1); \
;     if ((++_sp & 255u) == 0u) { if (xb_ld(&(bar)[XB_TMO])) break; if (_sp > XB_SPIN_CAP) { atomicAdd(&(bar)[XB_TMO], 1u); break; } } } } while (0)
; __device__ __forceinline__ void xcd_barrier(const XcdBarrier& b, bool leader) {
;     ...
;         XB_SPIN(xb_ld(&bar[XB_TOPGEN]) == gen, bar);
;         __builtin_amdgcn_fence(__ATOMIC_ACQUIRE, "agent");
;         asm volatile("s_waitcnt vmcnt(0)" ::: "memory");
.LBB0_387:
	s_or_b64 exec, exec, s[8:9]
	s_waitcnt vmcnt(0)
	s_waitcnt vmcnt(0)

; __device__ __forceinline__ unsigned xb_add(unsigned* p, unsigned v) { return __hip_atomic_fetch_add(p, v, __ATOMIC_RELAXED, __HIP_MEMORY_SCOPE_AGENT); }
; __device__ __forceinline__ void xcd_barrier(const XcdBarrier& b, bool leader) {
;     ...
;         const unsigned old = xb_add(&bar[XB_XSUB(b.x)], 1u);
;         const unsigned gen = old / nloc;
;         if (old + 1u == (gen + 1u) * nloc) {
;             __builtin_amdgcn_fence(__ATOMIC_RELEASE, "agent");
;             asm volatile("s_waitcnt vmcnt(0)" ::: "memory");
;             const unsigned og = xb_add(&bar[XB_TOP], 1u);
;             const unsigned tg = og / nx;
;             if (og + 1u == (tg + 1u) * nx) xb_add(&bar[XB_TOPGEN], 1u);
.LBB0_451:
	s_or_b64 exec, exec, s[10:11]
	v_cvt_f32_u32_e32 v4, v2
	s_waitcnt vmcnt(0)
	buffer_inv sc1
	v_readfirstlane_b32 s8, v3
	v_sub_u32_e32 v3, 0, v2
	v_rcp_iflag_f32_e32 v4, v4
	v_add_u32_e32 v5, s8, v0
	v_mul_f32_e32 v4, 0x4f7ffffe, v4
	v_cvt_u32_f32_e32 v4, v4
	v_mul_lo_u32 v0, v3, v4
	v_mul_hi_u32 v0, v4, v0
	v_add_u32_e32 v0, v4, v0
	v_mul_hi_u32 v0, v5, v0
	v_mul_lo_u32 v3, v0, v2
	v_sub_u32_e32 v3, v5, v3
	v_add_u32_e32 v4, 1, v0
	v_cmp_ge_u32_e32 vcc, v3, v2
	s_nop 1
	v_cndmask_b32_e32 v0, v0, v4, vcc
	v_sub_u32_e32 v4, v3, v2
	v_cndmask_b32_e32 v3, v3, v4, vcc
	v_add_u32_e32 v4, 1, v0
	v_cmp_ge_u32_e32 vcc, v3, v2
	v_add_u32_e32 v3, 1, v5
	s_nop 0
	v_cndmask_b32_e32 v0, v0, v4, vcc
	v_mul_lo_u32 v4, v2, v0
	v_add_u32_e32 v2, v4, v2
	v_cmp_eq_u32_e32 vcc, v3, v2
	s_and_saveexec_b64 s[8:9], vcc
	s_cbranch_execz .LBB0_457
	s_mov_b64 s[10:11], exec
	buffer_wbl2 sc1
	s_waitcnt lgkmcnt(0)
	s_waitcnt vmcnt(0)
	v_mbcnt_lo_u32_b32 v2, s10, 0
	v_mbcnt_hi_u32_b32 v2, s11, v2
	v_cmp_eq_u32_e32 vcc, 0, v2
	s_and_saveexec_b64 s[22:23], vcc
	s_cbranch_execz .LBB0_454
	s_bcnt1_i32_b64 s10, s[10:11]
	v_mov_b32_e32 v3, 0x3000
	v_mov_b32_e32 v4, s10
	global_atomic_add v3, v3, v4, s[90:91] offset:1024 sc0

; __device__ __forceinline__ unsigned xb_ld(unsigned* p)              { return __hip_atomic_load(p, __ATOMIC_RELAXED, __HIP_MEMORY_SCOPE_AGENT); }
; #define XB_SPIN(cond, bar) do { unsigned _sp = 0; while (cond) { __builtin_amdgcn_s_sleep(1); \
;     if ((++_sp & 255u) == 0u) { if (xb_ld(&(bar)[XB_TMO])) break; if (_sp > XB_SPIN_CAP) { atomicAdd(&(bar)[XB_TMO], 1u); break; } } } } while (0)
; __device__ __forceinline__ void xcd_barrier(const XcdBarrier& b, bool leader) {
;     ...
;         XB_SPIN(xb_ld(&bar[XB_TOPGEN]) == gen, bar);
;         __builtin_amdgcn_fence(__ATOMIC_ACQUIRE, "agent");
;         asm volatile("s_waitcnt vmcnt(0)" ::: "memory");
.LBB0_469:
	s_or_b64 exec, exec, s[8:9]
	s_waitcnt vmcnt(0)
	s_waitcnt vmcnt(0)
	v_mov_b64_e32 v[0:1], s[6:7]

; __device__ __forceinline__ unsigned xb_ld(unsigned* p)              { return __hip_atomic_load(p, __ATOMIC_RELAXED, __HIP_MEMORY_SCOPE_AGENT); }
; #define XB_SPIN(cond, bar) do { unsigned _sp = 0; while (cond) { __builtin_amdgcn_s_sleep(1); \
;     if ((++_sp & 255u) == 0u) { if (xb_ld(&(bar)[XB_TMO])) break; if (_sp > XB_SPIN_CAP) { atomicAdd(&(bar)[XB_TMO], 1u); break; } } } } while (0)
; __device__ __forceinline__ void xcd_barrier(const XcdBarrier& b, bool leader) {
;     ...
;         XB_SPIN(xb_ld(&bar[XB_TOPGEN]) == gen, bar);
;         __builtin_amdgcn_fence(__ATOMIC_ACQUIRE, "agent");
;         asm volatile("s_waitcnt vmcnt(0)" ::: "memory");
.LBB0_471:
	s_or_b64 exec, exec, s[10:11]
	s_waitcnt vmcnt(0)
	s_waitcnt vmcnt(0)

; __device__ __forceinline__ unsigned xb_add(unsigned* p, unsigned v) { return __hip_atomic_fetch_add(p, v, __ATOMIC_RELAXED, __HIP_MEMORY_SCOPE_AGENT); }
; __device__ __forceinline__ void xcd_barrier(const XcdBarrier& b, bool leader) {
;     ...
;         const unsigned old = xb_add(&bar[XB_XSUB(b.x)], 1u);
;         const unsigned gen = old / nloc;
;         if (old + 1u == (gen + 1u) * nloc) {
;             __builtin_amdgcn_fence(__ATOMIC_RELEASE, "agent");
;             asm volatile("s_waitcnt vmcnt(0)" ::: "memory");
;             const unsigned og = xb_add(&bar[XB_TOP], 1u);
;             const unsigned tg = og / nx;
;             if (og + 1u == (tg + 1u) * nx) xb_add(&bar[XB_TOPGEN], 1u);
.LBB0_537:
	global_atomic_add v3, v[144:145], v167, off sc0
	v_cvt_f32_u32_e32 v0, v2
	v_sub_u32_e32 v4, 0, v2
	v_rcp_iflag_f32_e32 v0, v0
	s_nop 0
	v_mul_f32_e32 v0, 0x4f7ffffe, v0
	v_cvt_u32_f32_e32 v0, v0
	v_mul_lo_u32 v4, v4, v0
	v_mul_hi_u32 v4, v0, v4
	v_add_u32_e32 v0, v0, v4
	s_waitcnt vmcnt(0)
	buffer_inv sc1
	v_mul_hi_u32 v0, v3, v0
	v_mul_lo_u32 v4, v0, v2
	v_sub_u32_e32 v4, v3, v4
	v_add_u32_e32 v5, 1, v0
	v_cmp_ge_u32_e32 vcc, v4, v2
	v_add_u32_e32 v3, 1, v3
	s_nop 0
	v_cndmask_b32_e32 v0, v0, v5, vcc
	v_sub_u32_e32 v5, v4, v2
	v_cndmask_b32_e32 v4, v4, v5, vcc
	v_add_u32_e32 v5, 1, v0
	v_cmp_ge_u32_e32 vcc, v4, v2
	s_nop 1
	v_cndmask_b32_e32 v0, v0, v5, vcc
	v_mul_lo_u32 v4, v2, v0
	v_add_u32_e32 v2, v4, v2
	v_cmp_eq_u32_e32 vcc, v3, v2
	s_and_saveexec_b64 s[10:11], vcc
	s_cbranch_execz .LBB0_543
	s_mov_b64 s[42:43], exec
	buffer_wbl2 sc1
	s_waitcnt lgkmcnt(0)
	s_waitcnt vmcnt(0)
	v_mbcnt_lo_u32_b32 v2, s42, 0
	v_mbcnt_hi_u32_b32 v2, s43, v2
	v_cmp_eq_u32_e32 vcc, 0, v2
	s_and_saveexec_b64 s[44:45], vcc
	s_cbranch_execz .LBB0_540
	s_bcnt1_i32_b64 s8, s[42:43]
	v_mov_b32_e32 v3, s8
	v_readlane_b32 s8, v249, 15
	v_readlane_b32 s9, v249, 16
	s_nop 4
	global_atomic_add v3, v147, v3, s[8:9] sc0
